# accumulators cleared by eight zero-operand 32x32x16 MFMAs instead of 64 v_mov_b64 (on top of prologue hoist)
# baseline (speedup 1.0000x reference)
.LBB0_245:
	s_ashr_i32 s69, s68, 31
	s_lshl_b64 s[56:57], s[68:69], 20
	s_add_u32 s33, s14, s56
	s_addc_u32 s48, s15, s57
	s_ashr_i32 s75, s74, 31
	s_lshl_b64 s[56:57], s[74:75], 7
	s_add_u32 s84, s33, s56
	s_addc_u32 s85, s48, s57
	s_and_b64 s[76:77], s[90:91], exec
	s_cselect_b32 s69, s85, s1
	s_cselect_b32 s75, s84, s0
	s_ashr_i32 s73, s72, 31
	s_lshl_b64 s[76:77], s[72:73], 20
	s_add_u32 s33, s9, s76
	s_addc_u32 s48, s23, s77
	s_add_u32 s86, s33, s56
	s_addc_u32 s87, s48, s57
	s_and_b64 s[56:57], s[90:91], exec
	s_cselect_b32 s73, s87, s89
	s_cselect_b32 vcc_lo, s86, s88
	s_add_i32 vcc_hi, s55, -2
	s_add_u32 s0, s0, 0x80080
	s_addc_u32 s1, s1, 0
	s_add_u32 s56, s88, 0x100
	s_addc_u32 s57, s89, 0
	s_mov_b32 s88, 0
	v_mov_b64_e32 v[222:223], 0
	v_mov_b64_e32 v[224:225], 0
	s_nop 1
	v_mfma_f32_32x32x16_bf16 v[4:19], v[222:225], v[222:225], 0
	v_mfma_f32_32x32x16_bf16 v[20:35], v[222:225], v[222:225], 0
	v_mfma_f32_32x32x16_bf16 v[36:51], v[222:225], v[222:225], 0
	v_mfma_f32_32x32x16_bf16 v[52:67], v[222:225], v[222:225], 0
	v_mfma_f32_32x32x16_bf16 v[68:83], v[222:225], v[222:225], 0
	v_mfma_f32_32x32x16_bf16 v[84:99], v[222:225], v[222:225], 0
	v_mfma_f32_32x32x16_bf16 v[100:115], v[222:225], v[222:225], 0
	v_mfma_f32_32x32x16_bf16 v[116:131], v[222:225], v[222:225], 0
	v_add_u32_e32 v246, 0x10000, v1
	v_add_u32_e32 v247, 0x14000, v1
	v_add_u32_e32 v248, 0x18000, v1
	v_add_u32_e32 v249, 0x1c000, v1

.LBB0_520:
	s_add_i32 s9, s64, -2
	s_add_u32 s74, s74, 0x80080
	s_addc_u32 s75, s75, 0
	s_add_u32 s23, s84, 0x100
	s_addc_u32 s35, s85, 0
	s_mov_b32 s54, 0
	v_mov_b64_e32 v[222:223], 0
	v_mov_b64_e32 v[224:225], 0
	s_nop 1
	v_mfma_f32_32x32x16_bf16 v[4:19], v[222:225], v[222:225], 0
	v_mfma_f32_32x32x16_bf16 v[20:35], v[222:225], v[222:225], 0
	v_mfma_f32_32x32x16_bf16 v[36:51], v[222:225], v[222:225], 0
	v_mfma_f32_32x32x16_bf16 v[52:67], v[222:225], v[222:225], 0
	v_mfma_f32_32x32x16_bf16 v[68:83], v[222:225], v[222:225], 0
	v_mfma_f32_32x32x16_bf16 v[84:99], v[222:225], v[222:225], 0
	v_mfma_f32_32x32x16_bf16 v[100:115], v[222:225], v[222:225], 0
	v_mfma_f32_32x32x16_bf16 v[116:131], v[222:225], v[222:225], 0
	v_add_u32_e32 v246, 0x10000, v142
	v_add_u32_e32 v247, 0x14000, v142
	v_add_u32_e32 v248, 0x18000, v142
	v_add_u32_e32 v249, 0x1c000, v142

.LBB0_693:
	s_ashr_i32 s75, s74, 31
	s_lshl_b64 s[16:17], s[74:75], 20
	s_add_u32 s84, s14, s16
	s_addc_u32 s85, s15, s17
	s_and_b64 s[16:17], s[36:37], exec
	s_cselect_b32 s16, s85, s89
	s_cselect_b32 s17, s84, s88
	s_ashr_i32 s73, s72, 31
	s_lshl_b64 s[50:51], s[72:73], 20
	s_add_u32 s86, s23, s50
	s_addc_u32 s87, s29, s51
	s_and_b64 s[50:51], s[36:37], exec
	s_cselect_b32 s50, s87, s91
	s_cselect_b32 s51, s86, s90
	s_add_u32 s88, s88, 0x80080
	s_addc_u32 s89, s89, 0
	s_add_u32 s54, s90, 0x100
	s_addc_u32 s55, s91, 0
	s_mov_b32 s56, -2
	v_mov_b64_e32 v[222:223], 0
	v_mov_b64_e32 v[224:225], 0
	s_nop 1
	v_mfma_f32_32x32x16_bf16 v[4:19], v[222:225], v[222:225], 0
	v_mfma_f32_32x32x16_bf16 v[20:35], v[222:225], v[222:225], 0
	v_mfma_f32_32x32x16_bf16 v[36:51], v[222:225], v[222:225], 0
	v_mfma_f32_32x32x16_bf16 v[52:67], v[222:225], v[222:225], 0
	v_mfma_f32_32x32x16_bf16 v[68:83], v[222:225], v[222:225], 0
	v_mfma_f32_32x32x16_bf16 v[84:99], v[222:225], v[222:225], 0
	v_mfma_f32_32x32x16_bf16 v[100:115], v[222:225], v[222:225], 0
	v_mfma_f32_32x32x16_bf16 v[116:131], v[222:225], v[222:225], 0
	v_add_u32_e32 v246, 0x10000, v144
	v_add_u32_e32 v247, 0x14000, v144
	v_add_u32_e32 v248, 0x18000, v144
	v_add_u32_e32 v249, 0x1c000, v144

.LBB0_762:
	s_add_i32 s23, s51, -2
	s_add_u32 s84, s84, 0x200080
	s_addc_u32 s85, s85, 0
	s_add_u32 s29, s86, 0x100
	s_addc_u32 s35, s87, 0
	s_mov_b32 s55, 0
	v_mov_b64_e32 v[222:223], 0
	v_mov_b64_e32 v[224:225], 0
	s_nop 1
	v_mfma_f32_32x32x16_bf16 v[4:19], v[222:225], v[222:225], 0
	v_mfma_f32_32x32x16_bf16 v[20:35], v[222:225], v[222:225], 0
	v_mfma_f32_32x32x16_bf16 v[36:51], v[222:225], v[222:225], 0
	v_mfma_f32_32x32x16_bf16 v[52:67], v[222:225], v[222:225], 0
	v_mfma_f32_32x32x16_bf16 v[68:83], v[222:225], v[222:225], 0
	v_mfma_f32_32x32x16_bf16 v[84:99], v[222:225], v[222:225], 0
	v_mfma_f32_32x32x16_bf16 v[100:115], v[222:225], v[222:225], 0
	v_mfma_f32_32x32x16_bf16 v[116:131], v[222:225], v[222:225], 0
	v_add_u32_e32 v246, 0x10000, v142
	v_add_u32_e32 v247, 0x14000, v142
	v_add_u32_e32 v248, 0x18000, v142
	v_add_u32_e32 v249, 0x1c000, v142
